# RWKV loader: each lane takes two consecutive tokens, so the second token's previous row is the first token's row (12 fewer VALU unpacks and 3 fewer loads per lane and chunk)
# speedup vs baseline: 1.0063x; 1.0063x over previous
; #define LAS __attribute__((address_space(3)))
; #define RW_LOAD(c) do { RW_LOAD1(c, 0); RW_LOAD1(c, 1); } while (0)
; #define RW_PROC(dst) do { RW_PROC1(dst, 0); RW_PROC1(dst, 1); } while (0)
; template <bool SAMPLE>
; __device__ __forceinline__ void rwkv_unit(PR P, LAS float* lds, const int b, const int h, const int half, const int wv) {
;     ...
;     RW_LOAD(0); RW_PROC(buf0); __syncthreads();
;     for (int c = 0; c < NCH; ++c) {
;         LAS float* cur = (c & 1) ? buf1 : buf0; LAS float* nxt = (c & 1) ? buf0 : buf1;
;         if (c + 1 < NCH) RW_LOAD(c + 1);
.LBB0_702:
	s_or_b64 exec, exec, s[8:9]
	v_ashrrev_i32_e32 v57, 6, v56
	s_lshl_b32 s8, s2, 5
	v_lshlrev_b32_e32 v21, 3, v57
	v_lshrrev_b32_e32 v56, 3, v54
	s_and_b32 s8, s8, 32
	v_and_b32_e32 v21, 24, v21
	v_and_b32_e32 v56, 6, v56
	v_and_b32_e32 v66, 15, v54
	v_or3_b32 v54, v56, s8, v21
	v_mov_b32_e32 v56, 0
	v_mov_b32_e32 v21, v56
	v_lshl_add_u64 v[58:59], s[12:13], 0, v[20:21]
	v_lshl_add_u64 v[60:61], s[10:11], 0, v[20:21]
	v_lshl_add_u64 v[62:63], s[14:15], 0, v[20:21]
	v_lshlrev_b32_e32 v20, 1, v54
	s_mov_b32 s71, 0
	v_lshl_add_u64 v[20:21], s[46:47], 0, v[20:21]
	s_lshl_b32 s70, s20, 1
	v_lshl_add_u64 v[20:21], v[20:21], 0, s[70:71]
	s_mov_b64 s[12:13], 0xbae4800
	v_lshlrev_b32_e32 v76, 2, v66
	v_cmp_gt_i32_e64 s[8:9], 4, v57
	v_or_b32_e32 v77, s6, v66
	v_lshl_add_u64 v[64:65], v[20:21], 0, s[12:13]
	v_and_b32_e32 v72, 3, v66
	v_cmp_eq_u32_e64 s[12:13], 0, v72
	v_cmp_eq_u32_e64 s[14:15], 1, v72
	v_cmp_eq_u32_e64 s[16:17], 2, v72
	s_movk_i32 s49, 0x1e00
	s_add_i32 s55, 0, 0xc000
	v_mov_b32_e32 v66, 0
	v_mov_b32_e32 v67, v56
	v_mov_b32_e32 v20, v56
	v_mov_b32_e32 v21, v56
	v_mov_b32_e32 v68, v56
	v_mov_b32_e32 v69, v56
	v_mov_b32_e32 v70, v56
	v_mov_b32_e32 v71, v56
	s_add_u32 s18, s46, 0x3d44800
	s_addc_u32 s19, s47, 0
	s_sub_u32 s20, s18, 0x1e00
	s_subb_u32 s21, s19, 0
	s_add_u32 s22, s46, 0xda04800
	s_addc_u32 s23, s47, 0
	s_add_u32 s24, s46, 0xea84800
	s_addc_u32 s25, s47, 0
	s_bfe_u32 s26, s2, 0x30001
	s_lshl_b32 s26, s26, 7
	v_lshrrev_b32_e32 v123, 1, v75
	v_add_u32_e32 v123, s26, v123
	v_mul_u32_u24_e32 v121, 0x3c00, v55
	v_add_u32_e32 v121, v121, v123
	v_lshl_add_u32 v122, v55, 11, v123
	v_lshl_add_u32 v123, v74, 1, v75
	s_cmp_lt_u32 s33, 0x100
	s_cbranch_scc1 .Lld_noprefetch
	s_mov_b32 s29, 1
	s_lshl_b32 s26, s29, 5
	s_add_i32 s26, s26, s6
	s_mul_i32 s27, s26, 0x1e00
	s_lshl_b32 s28, s26, 10
	v_add_u32_e32 v78, s27, v121
	v_add_u32_e32 v79, s28, v122
	global_load_dwordx2 v[124:125], v78, s[18:19]
	global_load_dwordx2 v[126:127], v78, s[18:19] offset:1024
	global_load_dwordx2 v[128:129], v78, s[18:19] offset:2048
	global_load_dwordx2 v[130:131], v78, s[20:21]
	global_load_dwordx2 v[132:133], v78, s[20:21] offset:1024
	global_load_dwordx2 v[134:135], v78, s[20:21] offset:2048
	global_load_dwordx2 v[136:137], v79, s[22:23]
	global_load_dwordx2 v[138:139], v79, s[24:25]
	s_add_u32 s27, s27, 0x1e00
	s_add_u32 s28, s28, 0x400
	v_add_u32_e32 v80, s27, v121
	v_add_u32_e32 v81, s28, v122
	global_load_dwordx2 v[140:141], v80, s[18:19]
	global_load_dwordx2 v[142:143], v80, s[18:19] offset:1024
	global_load_dwordx2 v[144:145], v80, s[18:19] offset:2048
	global_load_dwordx2 v[152:153], v81, s[22:23]
	global_load_dwordx2 v[154:155], v81, s[24:25]

; #define LAS __attribute__((address_space(3)))
; #define RW_LOAD(c) do { RW_LOAD1(c, 0); RW_LOAD1(c, 1); } while (0)
; template <bool SAMPLE>
; __device__ __forceinline__ void rwkv_unit(PR P, LAS float* lds, const int b, const int h, const int half, const int wv) {
;     ...
;     for (int c = 0; c < NCH; ++c) {
;         LAS float* cur = (c & 1) ? buf1 : buf0; LAS float* nxt = (c & 1) ? buf0 : buf1;
;         if (c + 1 < NCH) RW_LOAD(c + 1);
.LBB0_705:
	s_cmp_lt_u32 s33, 0x100
	s_cbranch_scc1 .Lrw_scan_chunk
	s_add_i32 s56, s71, 1
	s_cmp_eq_u32 s71, 63
	s_cbranch_scc1 .LBB0_704
	s_add_i32 s29, s56, 1
	s_bitcmp1_b32 s71, 0
	s_cbranch_scc1 .Lld_odd
	s_cmp_lt_u32 s29, 64
	s_cbranch_scc0 .Lld_last_even
	s_lshl_b32 s26, s29, 5
	s_add_i32 s26, s26, s6
	s_mul_i32 s27, s26, 0x1e00
	s_lshl_b32 s28, s26, 10
	v_add_u32_e32 v78, s27, v121
	v_add_u32_e32 v79, s28, v122
	global_load_dwordx2 v[22:23], v78, s[18:19]
	global_load_dwordx2 v[24:25], v78, s[18:19] offset:1024
	global_load_dwordx2 v[26:27], v78, s[18:19] offset:2048
	global_load_dwordx2 v[28:29], v78, s[20:21]
	global_load_dwordx2 v[30:31], v78, s[20:21] offset:1024
	global_load_dwordx2 v[32:33], v78, s[20:21] offset:2048
	global_load_dwordx2 v[34:35], v79, s[22:23]
	global_load_dwordx2 v[36:37], v79, s[24:25]
	s_add_u32 s27, s27, 0x1e00
	s_add_u32 s28, s28, 0x400
	v_add_u32_e32 v80, s27, v121
	v_add_u32_e32 v81, s28, v122
	global_load_dwordx2 v[38:39], v80, s[18:19]
	global_load_dwordx2 v[40:41], v80, s[18:19] offset:1024
	global_load_dwordx2 v[42:43], v80, s[18:19] offset:2048
	global_load_dwordx2 v[50:51], v81, s[22:23]
	global_load_dwordx2 v[52:53], v81, s[24:25]
	s_waitcnt vmcnt(13)
	s_branch .Lld_go_even

.Lld_go_even:
	s_bitcmp0_b32 s71, 0
	s_cselect_b32 s26, 0xc000, 0
	v_add_u32_e32 v80, s26, v123
	v_lshlrev_b32_e32 v156, 16, v124
	v_and_b32_e32 v157, 0xffff0000, v124
	v_lshlrev_b32_e32 v158, 16, v125
	v_and_b32_e32 v159, 0xffff0000, v125
	v_lshlrev_b32_e32 v108, 16, v130
	v_and_b32_e32 v109, 0xffff0000, v130
	v_lshlrev_b32_e32 v110, 16, v131
	v_and_b32_e32 v111, 0xffff0000, v131
	v_pk_add_f32 v[108:109], v[108:109], v[156:157] neg_lo:[0,1] neg_hi:[0,1]
	v_pk_add_f32 v[110:111], v[110:111], v[158:159] neg_lo:[0,1] neg_hi:[0,1]
	v_pk_fma_f32 v[84:85], v[0:1], v[108:109], v[156:157]
	v_pk_fma_f32 v[86:87], v[2:3], v[110:111], v[158:159]
	v_lshlrev_b32_e32 v160, 16, v126
	v_and_b32_e32 v161, 0xffff0000, v126
	v_lshlrev_b32_e32 v162, 16, v127
	v_and_b32_e32 v163, 0xffff0000, v127
	v_lshlrev_b32_e32 v108, 16, v132
	v_and_b32_e32 v109, 0xffff0000, v132
	v_lshlrev_b32_e32 v110, 16, v133
	v_and_b32_e32 v111, 0xffff0000, v133
	v_pk_add_f32 v[108:109], v[108:109], v[160:161] neg_lo:[0,1] neg_hi:[0,1]
	v_pk_add_f32 v[110:111], v[110:111], v[162:163] neg_lo:[0,1] neg_hi:[0,1]
	v_pk_fma_f32 v[88:89], v[12:13], v[108:109], v[160:161]
	v_pk_fma_f32 v[90:91], v[14:15], v[110:111], v[162:163]
	v_lshlrev_b32_e32 v164, 16, v128
	v_and_b32_e32 v165, 0xffff0000, v128
	v_lshlrev_b32_e32 v166, 16, v129
	v_and_b32_e32 v167, 0xffff0000, v129
	v_lshlrev_b32_e32 v108, 16, v134
	v_and_b32_e32 v109, 0xffff0000, v134
	v_lshlrev_b32_e32 v110, 16, v135
	v_and_b32_e32 v111, 0xffff0000, v135
	v_pk_add_f32 v[108:109], v[108:109], v[164:165] neg_lo:[0,1] neg_hi:[0,1]
	v_pk_add_f32 v[110:111], v[110:111], v[166:167] neg_lo:[0,1] neg_hi:[0,1]
	v_pk_fma_f32 v[92:93], v[4:5], v[108:109], v[164:165]
	v_pk_fma_f32 v[94:95], v[6:7], v[110:111], v[166:167]
	v_lshlrev_b32_e32 v96, 16, v136
	v_and_b32_e32 v97, 0xffff0000, v136
	v_lshlrev_b32_e32 v98, 16, v137
	v_and_b32_e32 v99, 0xffff0000, v137
	v_lshlrev_b32_e32 v100, 16, v138
	v_and_b32_e32 v101, 0xffff0000, v138
	v_lshlrev_b32_e32 v102, 16, v139
	v_and_b32_e32 v103, 0xffff0000, v139
	v_pk_mul_f32 v[112:113], v[8:9], v[88:89]
	v_pk_mul_f32 v[114:115], v[10:11], v[90:91]
	v_pk_mul_f32 v[104:105], v[112:113], v[112:113]
	v_pk_fma_f32 v[104:105], v[114:115], v[114:115], v[104:105]
	v_add_f32_e32 v104, v104, v105
	v_pk_add_f32 v[116:117], v[100:101], -1.0 op_sel_hi:[1,0]
	v_pk_add_f32 v[118:119], v[102:103], -1.0 op_sel_hi:[1,0]
	v_add_f32_dpp v104, v104, v104 quad_perm:[1,0,3,2] row_mask:0xf bank_mask:0xf bound_ctrl:1
	v_pk_fma_f32 v[116:117], v[16:17], v[116:117], 1.0 op_sel_hi:[1,1,0]
	v_pk_fma_f32 v[118:119], v[18:19], v[118:119], 1.0 op_sel_hi:[1,1,0]
	v_add_f32_dpp v104, v104, v104 quad_perm:[2,3,0,1] row_mask:0xf bank_mask:0xf bound_ctrl:1
	v_pk_mul_f32 v[116:117], v[116:117], v[88:89]
	v_pk_mul_f32 v[118:119], v[118:119], v[90:91]
	v_add_f32_dpp v104, v104, v104 row_half_mirror row_mask:0xf bank_mask:0xf bound_ctrl:1
	ds_write_b128 v80, v[84:87] offset:0
	ds_write_b128 v80, v[96:99] offset:256
	v_add_f32_dpp v104, v104, v104 row_mirror row_mask:0xf bank_mask:0xf bound_ctrl:1
	v_rsq_f32_e32 v104, v104
	ds_write_b128 v80, v[116:119] offset:512
	v_min_f32_e32 v104, 0x5368d4a5, v104
	v_pk_mul_f32 v[112:113], v[112:113], v[104:105] op_sel_hi:[1,0] neg_lo:[0,1] neg_hi:[0,1]
	v_pk_mul_f32 v[114:115], v[114:115], v[104:105] op_sel_hi:[1,0] neg_lo:[0,1] neg_hi:[0,1]
	ds_write_b128 v80, v[112:115] offset:768
	v_pk_mul_f32 v[108:109], v[112:113], v[100:101] neg_lo:[1,0] neg_hi:[1,0]
	v_pk_mul_f32 v[110:111], v[114:115], v[102:103] neg_lo:[1,0] neg_hi:[1,0]
	ds_write_b128 v80, v[108:111] offset:1024
	ds_write_b128 v80, v[92:95] offset:1280
	v_lshlrev_b32_e32 v104, 16, v140
	v_and_b32_e32 v105, 0xffff0000, v140
	v_lshlrev_b32_e32 v106, 16, v141
	v_and_b32_e32 v107, 0xffff0000, v141
	v_pk_add_f32 v[108:109], v[156:157], v[104:105] neg_lo:[0,1] neg_hi:[0,1]
	v_pk_add_f32 v[110:111], v[158:159], v[106:107] neg_lo:[0,1] neg_hi:[0,1]
	v_pk_fma_f32 v[84:85], v[0:1], v[108:109], v[104:105]
	v_pk_fma_f32 v[86:87], v[2:3], v[110:111], v[106:107]
	v_lshlrev_b32_e32 v104, 16, v142
	v_and_b32_e32 v105, 0xffff0000, v142
	v_lshlrev_b32_e32 v106, 16, v143
	v_and_b32_e32 v107, 0xffff0000, v143
	v_pk_add_f32 v[108:109], v[160:161], v[104:105] neg_lo:[0,1] neg_hi:[0,1]
	v_pk_add_f32 v[110:111], v[162:163], v[106:107] neg_lo:[0,1] neg_hi:[0,1]
	v_pk_fma_f32 v[88:89], v[12:13], v[108:109], v[104:105]
	v_pk_fma_f32 v[90:91], v[14:15], v[110:111], v[106:107]
	v_lshlrev_b32_e32 v104, 16, v144
	v_and_b32_e32 v105, 0xffff0000, v144
	v_lshlrev_b32_e32 v106, 16, v145
	v_and_b32_e32 v107, 0xffff0000, v145
	v_pk_add_f32 v[108:109], v[164:165], v[104:105] neg_lo:[0,1] neg_hi:[0,1]
	v_pk_add_f32 v[110:111], v[166:167], v[106:107] neg_lo:[0,1] neg_hi:[0,1]
	v_pk_fma_f32 v[92:93], v[4:5], v[108:109], v[104:105]
	v_pk_fma_f32 v[94:95], v[6:7], v[110:111], v[106:107]
	v_lshlrev_b32_e32 v96, 16, v152
	v_and_b32_e32 v97, 0xffff0000, v152
	v_lshlrev_b32_e32 v98, 16, v153
	v_and_b32_e32 v99, 0xffff0000, v153
	v_lshlrev_b32_e32 v100, 16, v154
	v_and_b32_e32 v101, 0xffff0000, v154
	v_lshlrev_b32_e32 v102, 16, v155
	v_and_b32_e32 v103, 0xffff0000, v155
	v_pk_mul_f32 v[112:113], v[8:9], v[88:89]
	v_pk_mul_f32 v[114:115], v[10:11], v[90:91]
	v_pk_mul_f32 v[104:105], v[112:113], v[112:113]
	v_pk_fma_f32 v[104:105], v[114:115], v[114:115], v[104:105]
	v_add_f32_e32 v104, v104, v105
	v_pk_add_f32 v[116:117], v[100:101], -1.0 op_sel_hi:[1,0]
	v_pk_add_f32 v[118:119], v[102:103], -1.0 op_sel_hi:[1,0]
	v_add_f32_dpp v104, v104, v104 quad_perm:[1,0,3,2] row_mask:0xf bank_mask:0xf bound_ctrl:1
	v_pk_fma_f32 v[116:117], v[16:17], v[116:117], 1.0 op_sel_hi:[1,1,0]
	v_pk_fma_f32 v[118:119], v[18:19], v[118:119], 1.0 op_sel_hi:[1,1,0]
	v_add_f32_dpp v104, v104, v104 quad_perm:[2,3,0,1] row_mask:0xf bank_mask:0xf bound_ctrl:1
	v_pk_mul_f32 v[116:117], v[116:117], v[88:89]
	v_pk_mul_f32 v[118:119], v[118:119], v[90:91]
	v_add_f32_dpp v104, v104, v104 row_half_mirror row_mask:0xf bank_mask:0xf bound_ctrl:1
	ds_write_b128 v80, v[84:87] offset:1536
	ds_write_b128 v80, v[96:99] offset:1792
	v_add_f32_dpp v104, v104, v104 row_mirror row_mask:0xf bank_mask:0xf bound_ctrl:1
	v_rsq_f32_e32 v104, v104
	ds_write_b128 v80, v[116:119] offset:2048
	v_min_f32_e32 v104, 0x5368d4a5, v104
	v_pk_mul_f32 v[112:113], v[112:113], v[104:105] op_sel_hi:[1,0] neg_lo:[0,1] neg_hi:[0,1]
	v_pk_mul_f32 v[114:115], v[114:115], v[104:105] op_sel_hi:[1,0] neg_lo:[0,1] neg_hi:[0,1]
	ds_write_b128 v80, v[112:115] offset:2304
	v_pk_mul_f32 v[108:109], v[112:113], v[100:101] neg_lo:[1,0] neg_hi:[1,0]
	v_pk_mul_f32 v[110:111], v[114:115], v[102:103] neg_lo:[1,0] neg_hi:[1,0]
	ds_write_b128 v80, v[108:111] offset:2560
	ds_write_b128 v80, v[92:95] offset:2816
	s_branch .LBB0_704
.Lld_odd:
	s_cmp_lt_u32 s29, 64
	s_cbranch_scc0 .Lld_last_odd
	s_lshl_b32 s26, s29, 5
	s_add_i32 s26, s26, s6
	s_mul_i32 s27, s26, 0x1e00
	s_lshl_b32 s28, s26, 10
	v_add_u32_e32 v78, s27, v121
	v_add_u32_e32 v79, s28, v122
	global_load_dwordx2 v[124:125], v78, s[18:19]
	global_load_dwordx2 v[126:127], v78, s[18:19] offset:1024
	global_load_dwordx2 v[128:129], v78, s[18:19] offset:2048
	global_load_dwordx2 v[130:131], v78, s[20:21]
	global_load_dwordx2 v[132:133], v78, s[20:21] offset:1024
	global_load_dwordx2 v[134:135], v78, s[20:21] offset:2048
	global_load_dwordx2 v[136:137], v79, s[22:23]
	global_load_dwordx2 v[138:139], v79, s[24:25]
	s_add_u32 s27, s27, 0x1e00
	s_add_u32 s28, s28, 0x400
	v_add_u32_e32 v80, s27, v121
	v_add_u32_e32 v81, s28, v122
	global_load_dwordx2 v[140:141], v80, s[18:19]
	global_load_dwordx2 v[142:143], v80, s[18:19] offset:1024
	global_load_dwordx2 v[144:145], v80, s[18:19] offset:2048
	global_load_dwordx2 v[152:153], v81, s[22:23]
	global_load_dwordx2 v[154:155], v81, s[24:25]
	s_waitcnt vmcnt(13)
	s_branch .Lld_go_odd

.Lld_go_odd:
	s_bitcmp0_b32 s71, 0
	s_cselect_b32 s26, 0xc000, 0
	v_add_u32_e32 v80, s26, v123
	v_lshlrev_b32_e32 v156, 16, v22
	v_and_b32_e32 v157, 0xffff0000, v22
	v_lshlrev_b32_e32 v158, 16, v23
	v_and_b32_e32 v159, 0xffff0000, v23
	v_lshlrev_b32_e32 v108, 16, v28
	v_and_b32_e32 v109, 0xffff0000, v28
	v_lshlrev_b32_e32 v110, 16, v29
	v_and_b32_e32 v111, 0xffff0000, v29
	v_pk_add_f32 v[108:109], v[108:109], v[156:157] neg_lo:[0,1] neg_hi:[0,1]
	v_pk_add_f32 v[110:111], v[110:111], v[158:159] neg_lo:[0,1] neg_hi:[0,1]
	v_pk_fma_f32 v[84:85], v[0:1], v[108:109], v[156:157]
	v_pk_fma_f32 v[86:87], v[2:3], v[110:111], v[158:159]
	v_lshlrev_b32_e32 v160, 16, v24
	v_and_b32_e32 v161, 0xffff0000, v24
	v_lshlrev_b32_e32 v162, 16, v25
	v_and_b32_e32 v163, 0xffff0000, v25
	v_lshlrev_b32_e32 v108, 16, v30
	v_and_b32_e32 v109, 0xffff0000, v30
	v_lshlrev_b32_e32 v110, 16, v31
	v_and_b32_e32 v111, 0xffff0000, v31
	v_pk_add_f32 v[108:109], v[108:109], v[160:161] neg_lo:[0,1] neg_hi:[0,1]
	v_pk_add_f32 v[110:111], v[110:111], v[162:163] neg_lo:[0,1] neg_hi:[0,1]
	v_pk_fma_f32 v[88:89], v[12:13], v[108:109], v[160:161]
	v_pk_fma_f32 v[90:91], v[14:15], v[110:111], v[162:163]
	v_lshlrev_b32_e32 v164, 16, v26
	v_and_b32_e32 v165, 0xffff0000, v26
	v_lshlrev_b32_e32 v166, 16, v27
	v_and_b32_e32 v167, 0xffff0000, v27
	v_lshlrev_b32_e32 v108, 16, v32
	v_and_b32_e32 v109, 0xffff0000, v32
	v_lshlrev_b32_e32 v110, 16, v33
	v_and_b32_e32 v111, 0xffff0000, v33
	v_pk_add_f32 v[108:109], v[108:109], v[164:165] neg_lo:[0,1] neg_hi:[0,1]
	v_pk_add_f32 v[110:111], v[110:111], v[166:167] neg_lo:[0,1] neg_hi:[0,1]
	v_pk_fma_f32 v[92:93], v[4:5], v[108:109], v[164:165]
	v_pk_fma_f32 v[94:95], v[6:7], v[110:111], v[166:167]
	v_lshlrev_b32_e32 v96, 16, v34
	v_and_b32_e32 v97, 0xffff0000, v34
	v_lshlrev_b32_e32 v98, 16, v35
	v_and_b32_e32 v99, 0xffff0000, v35
	v_lshlrev_b32_e32 v100, 16, v36
	v_and_b32_e32 v101, 0xffff0000, v36
	v_lshlrev_b32_e32 v102, 16, v37
	v_and_b32_e32 v103, 0xffff0000, v37
	v_pk_mul_f32 v[112:113], v[8:9], v[88:89]
	v_pk_mul_f32 v[114:115], v[10:11], v[90:91]
	v_pk_mul_f32 v[104:105], v[112:113], v[112:113]
	v_pk_fma_f32 v[104:105], v[114:115], v[114:115], v[104:105]
	v_add_f32_e32 v104, v104, v105
	v_pk_add_f32 v[116:117], v[100:101], -1.0 op_sel_hi:[1,0]
	v_pk_add_f32 v[118:119], v[102:103], -1.0 op_sel_hi:[1,0]
	v_add_f32_dpp v104, v104, v104 quad_perm:[1,0,3,2] row_mask:0xf bank_mask:0xf bound_ctrl:1
	v_pk_fma_f32 v[116:117], v[16:17], v[116:117], 1.0 op_sel_hi:[1,1,0]
	v_pk_fma_f32 v[118:119], v[18:19], v[118:119], 1.0 op_sel_hi:[1,1,0]
	v_add_f32_dpp v104, v104, v104 quad_perm:[2,3,0,1] row_mask:0xf bank_mask:0xf bound_ctrl:1
	v_pk_mul_f32 v[116:117], v[116:117], v[88:89]
	v_pk_mul_f32 v[118:119], v[118:119], v[90:91]
	v_add_f32_dpp v104, v104, v104 row_half_mirror row_mask:0xf bank_mask:0xf bound_ctrl:1
	ds_write_b128 v80, v[84:87] offset:0
	ds_write_b128 v80, v[96:99] offset:256
	v_add_f32_dpp v104, v104, v104 row_mirror row_mask:0xf bank_mask:0xf bound_ctrl:1
	v_rsq_f32_e32 v104, v104
	ds_write_b128 v80, v[116:119] offset:512
	v_min_f32_e32 v104, 0x5368d4a5, v104
	v_pk_mul_f32 v[112:113], v[112:113], v[104:105] op_sel_hi:[1,0] neg_lo:[0,1] neg_hi:[0,1]
	v_pk_mul_f32 v[114:115], v[114:115], v[104:105] op_sel_hi:[1,0] neg_lo:[0,1] neg_hi:[0,1]
	ds_write_b128 v80, v[112:115] offset:768
	v_pk_mul_f32 v[108:109], v[112:113], v[100:101] neg_lo:[1,0] neg_hi:[1,0]
	v_pk_mul_f32 v[110:111], v[114:115], v[102:103] neg_lo:[1,0] neg_hi:[1,0]
	ds_write_b128 v80, v[108:111] offset:1024
	ds_write_b128 v80, v[92:95] offset:1280
	v_lshlrev_b32_e32 v104, 16, v38
	v_and_b32_e32 v105, 0xffff0000, v38
	v_lshlrev_b32_e32 v106, 16, v39
	v_and_b32_e32 v107, 0xffff0000, v39
	v_pk_add_f32 v[108:109], v[156:157], v[104:105] neg_lo:[0,1] neg_hi:[0,1]
	v_pk_add_f32 v[110:111], v[158:159], v[106:107] neg_lo:[0,1] neg_hi:[0,1]
	v_pk_fma_f32 v[84:85], v[0:1], v[108:109], v[104:105]
	v_pk_fma_f32 v[86:87], v[2:3], v[110:111], v[106:107]
	v_lshlrev_b32_e32 v104, 16, v40
	v_and_b32_e32 v105, 0xffff0000, v40
	v_lshlrev_b32_e32 v106, 16, v41
	v_and_b32_e32 v107, 0xffff0000, v41
	v_pk_add_f32 v[108:109], v[160:161], v[104:105] neg_lo:[0,1] neg_hi:[0,1]
	v_pk_add_f32 v[110:111], v[162:163], v[106:107] neg_lo:[0,1] neg_hi:[0,1]
	v_pk_fma_f32 v[88:89], v[12:13], v[108:109], v[104:105]
	v_pk_fma_f32 v[90:91], v[14:15], v[110:111], v[106:107]
	v_lshlrev_b32_e32 v104, 16, v42
	v_and_b32_e32 v105, 0xffff0000, v42
	v_lshlrev_b32_e32 v106, 16, v43
	v_and_b32_e32 v107, 0xffff0000, v43
	v_pk_add_f32 v[108:109], v[164:165], v[104:105] neg_lo:[0,1] neg_hi:[0,1]
	v_pk_add_f32 v[110:111], v[166:167], v[106:107] neg_lo:[0,1] neg_hi:[0,1]
	v_pk_fma_f32 v[92:93], v[4:5], v[108:109], v[104:105]
	v_pk_fma_f32 v[94:95], v[6:7], v[110:111], v[106:107]
	v_lshlrev_b32_e32 v96, 16, v50
	v_and_b32_e32 v97, 0xffff0000, v50
	v_lshlrev_b32_e32 v98, 16, v51
	v_and_b32_e32 v99, 0xffff0000, v51
	v_lshlrev_b32_e32 v100, 16, v52
	v_and_b32_e32 v101, 0xffff0000, v52
	v_lshlrev_b32_e32 v102, 16, v53
	v_and_b32_e32 v103, 0xffff0000, v53
	v_pk_mul_f32 v[112:113], v[8:9], v[88:89]
	v_pk_mul_f32 v[114:115], v[10:11], v[90:91]
	v_pk_mul_f32 v[104:105], v[112:113], v[112:113]
	v_pk_fma_f32 v[104:105], v[114:115], v[114:115], v[104:105]
	v_add_f32_e32 v104, v104, v105
	v_pk_add_f32 v[116:117], v[100:101], -1.0 op_sel_hi:[1,0]
	v_pk_add_f32 v[118:119], v[102:103], -1.0 op_sel_hi:[1,0]
	v_add_f32_dpp v104, v104, v104 quad_perm:[1,0,3,2] row_mask:0xf bank_mask:0xf bound_ctrl:1
	v_pk_fma_f32 v[116:117], v[16:17], v[116:117], 1.0 op_sel_hi:[1,1,0]
	v_pk_fma_f32 v[118:119], v[18:19], v[118:119], 1.0 op_sel_hi:[1,1,0]
	v_add_f32_dpp v104, v104, v104 quad_perm:[2,3,0,1] row_mask:0xf bank_mask:0xf bound_ctrl:1
	v_pk_mul_f32 v[116:117], v[116:117], v[88:89]
	v_pk_mul_f32 v[118:119], v[118:119], v[90:91]
	v_add_f32_dpp v104, v104, v104 row_half_mirror row_mask:0xf bank_mask:0xf bound_ctrl:1
	ds_write_b128 v80, v[84:87] offset:1536
	ds_write_b128 v80, v[96:99] offset:1792
	v_add_f32_dpp v104, v104, v104 row_mirror row_mask:0xf bank_mask:0xf bound_ctrl:1
	v_rsq_f32_e32 v104, v104
	ds_write_b128 v80, v[116:119] offset:2048
	v_min_f32_e32 v104, 0x5368d4a5, v104
	v_pk_mul_f32 v[112:113], v[112:113], v[104:105] op_sel_hi:[1,0] neg_lo:[0,1] neg_hi:[0,1]
	v_pk_mul_f32 v[114:115], v[114:115], v[104:105] op_sel_hi:[1,0] neg_lo:[0,1] neg_hi:[0,1]
	ds_write_b128 v80, v[112:115] offset:2304
	v_pk_mul_f32 v[108:109], v[112:113], v[100:101] neg_lo:[1,0] neg_hi:[1,0]
	v_pk_mul_f32 v[110:111], v[114:115], v[102:103] neg_lo:[1,0] neg_hi:[1,0]
	ds_write_b128 v80, v[108:111] offset:2560
	ds_write_b128 v80, v[92:95] offset:2816
	s_branch .LBB0_704
